# grid barrier: non-leader workgroups poll the cross-XCD release word directly (one serial hop fewer per barrier) on top of opt14
# baseline (speedup 1.0000x reference)
; __device__ __forceinline__ unsigned xb_ld(unsigned* p)              { return __hip_atomic_load(p, __ATOMIC_RELAXED, __HIP_MEMORY_SCOPE_AGENT); }
; __device__ __forceinline__ unsigned xb_add(unsigned* p, unsigned v) { return __hip_atomic_fetch_add(p, v, __ATOMIC_RELAXED, __HIP_MEMORY_SCOPE_AGENT); }
; #define XB_SPIN(cond, bar) do { unsigned _sp = 0; while (cond) { __builtin_amdgcn_s_sleep(1); \
;     if ((++_sp & 255u) == 0u) { if (xb_ld(&(bar)[XB_TMO])) break; if (_sp > XB_SPIN_CAP) { atomicAdd(&(bar)[XB_TMO], 1u); break; } } } } while (0)
; __device__ __forceinline__ void xcd_barrier(const XcdBarrier& b) {
;     ...
;         const unsigned old = xb_add(&bar[XB_XSUB(b.x)], 1u);
;         const unsigned gen = old / nloc;
;         if (old + 1u == (gen + 1u) * nloc) {
;             __builtin_amdgcn_fence(__ATOMIC_RELEASE, "agent");
;             asm volatile("s_waitcnt vmcnt(0)" ::: "memory");
;             const unsigned og = xb_add(&bar[XB_TOP], 1u);
;             const unsigned tg = og / nx;
;             if (og + 1u == (tg + 1u) * nx) xb_add(&bar[XB_TOPGEN], 1u);
;             else XB_SPIN(xb_ld(&bar[XB_TOPGEN]) == tg, bar);
;             __builtin_amdgcn_fence(__ATOMIC_ACQUIRE, "agent");
;             xb_add(&bar[XB_XGEN(b.x)], 1u);
;             asm volatile("s_waitcnt vmcnt(0)" ::: "memory");
;         } else {
;             XB_SPIN(xb_ld(&bar[XB_XGEN(b.x)]) == gen, bar);
;             __builtin_amdgcn_fence(__ATOMIC_ACQUIRE, "agent");
;             asm volatile("s_waitcnt vmcnt(0)" ::: "memory");
.LBB0_533:
	s_or_b64 exec, exec, s[12:13]
	v_cvt_f32_u32_e32 v5, v3
	s_waitcnt vmcnt(0)
	v_readfirstlane_b32 s2, v4
	v_sub_u32_e32 v4, 0, v3
	v_rcp_iflag_f32_e32 v5, v5
	v_add_u32_e32 v6, s2, v2
	v_mul_f32_e32 v5, 0x4f7ffffe, v5
	v_cvt_u32_f32_e32 v5, v5
	v_mul_lo_u32 v2, v4, v5
	v_mul_hi_u32 v2, v5, v2
	v_add_u32_e32 v2, v5, v2
	v_mul_hi_u32 v2, v6, v2
	v_mul_lo_u32 v4, v2, v3
	v_sub_u32_e32 v4, v6, v4
	v_add_u32_e32 v5, 1, v2
	v_cmp_ge_u32_e32 vcc, v4, v3
	s_nop 1
	v_cndmask_b32_e32 v2, v2, v5, vcc
	v_sub_u32_e32 v5, v4, v3
	v_cndmask_b32_e32 v4, v4, v5, vcc
	v_add_u32_e32 v5, 1, v2
	v_cmp_ge_u32_e32 vcc, v4, v3
	v_add_u32_e32 v4, 1, v6
	s_nop 0
	v_cndmask_b32_e32 v2, v2, v5, vcc
	v_mul_lo_u32 v5, v3, v2
	v_add_u32_e32 v3, v5, v3
	v_cmp_ne_u32_e32 vcc, v4, v3
	s_and_saveexec_b64 s[10:11], vcc
	s_xor_b64 s[10:11], exec, s[10:11]
	s_cbranch_execz .LBB0_547
	s_waitcnt lgkmcnt(0)
	s_add_u32 s16, s6, 0x32c03500
	s_addc_u32 s17, s7, 0
	s_add_i32 s2, s80, -1
	v_mov_b32_e32 v2, s2
	global_load_dword v0, v1, s[16:17] sc1
	s_waitcnt vmcnt(0)
	v_cmp_eq_u32_e32 vcc, v0, v2
	s_and_saveexec_b64 s[12:13], vcc
	s_cbranch_execz .LBB0_546
	s_add_u32 s14, s6, 0x32c00200
	s_addc_u32 s15, s7, 0
	s_mov_b32 s2, 1
	s_mov_b64 s[18:19], 0
	s_branch .LBB0_537
